# v32 + out-proj/FFN-out GEMM: the last k-iteration runs from a copy without the 14 dummy next-unit LDS-DMA prefetch loads (those units never have a successor)
# speedup vs baseline: 1.0019x; 1.0019x over previous
.LBB0_1179:
	s_add_i32 s92, s42, 2
	s_add_u32 s72, s36, 0x80
	s_addc_u32 s43, s37, 0
	s_add_i32 s93, 0, 0x10000
	v_add_u32_e32 v1, s93, v223
	ds_read_b128 v[50:53], v1
	ds_read_b128 v[54:57], v1 offset:1024
	ds_read_b128 v[58:61], v1 offset:2048
	ds_read_b128 v[62:65], v1 offset:3072
	s_cmp_eq_u32 s88, s42
	s_cselect_b32 s42, s66, s72
	s_cselect_b32 s43, s67, s43
	s_cselect_b32 s73, s71, s91
	s_cselect_b32 s72, s70, s27
	v_lshl_add_u64 v[178:179], s[36:37], 0, v[206:207]
	s_add_i32 m0, s79, 0xc000
	ds_read_b128 v[66:69], v230
	ds_read_b128 v[70:73], v230 offset:1024
	ds_read_b128 v[74:77], v230 offset:2048
	ds_read_b128 v[78:81], v230 offset:3072
	ds_read_b128 v[146:149], v230 offset:4096
	ds_read_b128 v[154:157], v230 offset:5120
	ds_read_b128 v[170:173], v230 offset:6144
	ds_read_b128 v[174:177], v230 offset:7168
	global_load_lds_dwordx4 v[178:179], off
	v_lshl_add_u64 v[178:179], s[36:37], 0, v[204:205]
	s_add_i32 m0, s79, 0xe000
	s_nop 0
	global_load_lds_dwordx4 v[178:179], off
	s_waitcnt lgkmcnt(8)
	s_barrier
	s_waitcnt lgkmcnt(0)
	s_waitcnt lgkmcnt(0)
	v_mfma_f32_16x16x32_bf16 v[166:169], v[50:53], v[66:69], v[166:169]
	v_mfma_f32_16x16x32_bf16 v[162:165], v[58:61], v[66:69], v[162:165]
	v_mfma_f32_16x16x32_bf16 v[142:145], v[50:53], v[74:77], v[142:145]
	v_mfma_f32_16x16x32_bf16 v[138:141], v[58:61], v[74:77], v[138:141]
	v_mfma_f32_16x16x32_bf16 v[126:129], v[50:53], v[146:149], v[126:129]
	v_mfma_f32_16x16x32_bf16 v[122:125], v[58:61], v[146:149], v[122:125]
	v_mfma_f32_16x16x32_bf16 v[110:113], v[50:53], v[170:173], v[110:113]
	v_mfma_f32_16x16x32_bf16 v[106:109], v[58:61], v[170:173], v[106:109]
	v_mfma_f32_16x16x32_bf16 v[166:169], v[54:57], v[70:73], v[166:169]
	v_mfma_f32_16x16x32_bf16 v[162:165], v[62:65], v[70:73], v[162:165]
	v_mfma_f32_16x16x32_bf16 v[142:145], v[54:57], v[78:81], v[142:145]
	v_mfma_f32_16x16x32_bf16 v[138:141], v[62:65], v[78:81], v[138:141]
	v_mfma_f32_16x16x32_bf16 v[126:129], v[54:57], v[154:157], v[126:129]
	v_mfma_f32_16x16x32_bf16 v[122:125], v[62:65], v[154:157], v[122:125]
	v_mfma_f32_16x16x32_bf16 v[110:113], v[54:57], v[174:177], v[110:113]
	v_mfma_f32_16x16x32_bf16 v[106:109], v[62:65], v[174:177], v[106:109]
	s_barrier
	s_add_i32 s94, 0, 0x14000
	s_add_i32 s93, s93, s78
	v_add_u32_e32 v1, s94, v223
	v_lshl_add_u64 v[214:215], s[72:73], 0, v[202:203]
	s_mov_b32 m0, s93
	ds_read_b128 v[178:181], v1
	ds_read_b128 v[182:185], v1 offset:1024
	ds_read_b128 v[186:189], v1 offset:2048
	ds_read_b128 v[190:193], v1 offset:3072
	global_load_lds_dwordx4 v[214:215], off
	v_lshl_add_u64 v[236:237], s[72:73], 0, v[200:201]
	s_add_i32 m0, s93, 0x2000
	s_nop 0
	global_load_lds_dwordx4 v[236:237], off
	s_barrier
	s_waitcnt lgkmcnt(0)
	s_waitcnt lgkmcnt(0)
	v_mfma_f32_16x16x32_bf16 v[158:161], v[178:181], v[66:69], v[158:161]
	v_mfma_f32_16x16x32_bf16 v[66:69], v[186:189], v[66:69], v[150:153]
	v_mfma_f32_16x16x32_bf16 v[158:161], v[182:185], v[70:73], v[158:161]
	v_mfma_f32_16x16x32_bf16 v[66:69], v[190:193], v[70:73], v[66:69]
	v_mfma_f32_16x16x32_bf16 v[70:73], v[178:181], v[74:77], v[134:137]
	v_mfma_f32_16x16x32_bf16 v[74:77], v[186:189], v[74:77], v[130:133]
	v_mfma_f32_16x16x32_bf16 v[114:117], v[186:189], v[146:149], v[114:117]
	v_mfma_f32_16x16x32_bf16 v[102:105], v[178:181], v[170:173], v[102:105]
	v_mfma_f32_16x16x32_bf16 v[98:101], v[186:189], v[170:173], v[98:101]
	v_mfma_f32_16x16x32_bf16 v[70:73], v[182:185], v[78:81], v[70:73]
	v_mfma_f32_16x16x32_bf16 v[74:77], v[190:193], v[78:81], v[74:77]
	v_mfma_f32_16x16x32_bf16 v[78:81], v[178:181], v[146:149], v[118:121]
	v_mfma_f32_16x16x32_bf16 v[114:117], v[190:193], v[154:157], v[114:117]
	v_mfma_f32_16x16x32_bf16 v[102:105], v[182:185], v[174:177], v[102:105]
	v_mfma_f32_16x16x32_bf16 v[98:101], v[190:193], v[174:177], v[98:101]
	v_mfma_f32_16x16x32_bf16 v[78:81], v[182:185], v[154:157], v[78:81]
	s_mov_b32 m0, s79
	v_lshl_add_u64 v[238:239], s[42:43], 0, v[202:203]
	s_barrier
	ds_read_b128 v[118:121], v230 offset:16384
	ds_read_b128 v[130:133], v230 offset:17408
	ds_read_b128 v[134:137], v230 offset:18432
	ds_read_b128 v[146:149], v230 offset:19456
	ds_read_b128 v[150:153], v230 offset:20480
	ds_read_b128 v[154:157], v230 offset:21504
	ds_read_b128 v[170:173], v230 offset:22528
	ds_read_b128 v[174:177], v230 offset:23552
	global_load_lds_dwordx4 v[238:239], off
	v_lshl_add_u64 v[240:241], s[42:43], 0, v[200:201]
	s_mov_b32 m0, s80
	s_nop 0
	global_load_lds_dwordx4 v[240:241], off
	s_barrier
	s_waitcnt lgkmcnt(0)
	s_waitcnt lgkmcnt(0)
	v_mfma_f32_16x16x32_bf16 v[94:97], v[50:53], v[118:121], v[94:97]
	v_mfma_f32_16x16x32_bf16 v[90:93], v[58:61], v[118:121], v[90:93]
	v_mfma_f32_16x16x32_bf16 v[46:49], v[50:53], v[134:137], v[46:49]
	v_mfma_f32_16x16x32_bf16 v[42:45], v[58:61], v[134:137], v[42:45]
	v_mfma_f32_16x16x32_bf16 v[30:33], v[50:53], v[150:153], v[30:33]
	v_mfma_f32_16x16x32_bf16 v[26:29], v[58:61], v[150:153], v[26:29]
	v_mfma_f32_16x16x32_bf16 v[14:17], v[50:53], v[170:173], v[14:17]
	v_mfma_f32_16x16x32_bf16 v[10:13], v[58:61], v[170:173], v[10:13]
	v_mfma_f32_16x16x32_bf16 v[94:97], v[54:57], v[130:133], v[94:97]
	v_mfma_f32_16x16x32_bf16 v[90:93], v[62:65], v[130:133], v[90:93]
	v_mfma_f32_16x16x32_bf16 v[46:49], v[54:57], v[146:149], v[46:49]
	v_mfma_f32_16x16x32_bf16 v[42:45], v[62:65], v[146:149], v[42:45]
	v_mfma_f32_16x16x32_bf16 v[30:33], v[54:57], v[154:157], v[30:33]
	v_mfma_f32_16x16x32_bf16 v[26:29], v[62:65], v[154:157], v[26:29]
	v_mfma_f32_16x16x32_bf16 v[14:17], v[54:57], v[174:177], v[14:17]
	v_mfma_f32_16x16x32_bf16 v[10:13], v[62:65], v[174:177], v[10:13]
	s_barrier
	s_add_u32 s72, s72, s4
	s_addc_u32 s73, s73, 0
	s_add_i32 s93, s94, s78
	v_lshl_add_u64 v[242:243], s[72:73], 0, v[202:203]
	s_mov_b32 m0, s93
	v_lshl_add_u64 v[244:245], s[72:73], 0, v[200:201]
	global_load_lds_dwordx4 v[242:243], off
	s_add_i32 m0, s93, 0x2000
	s_nop 0
	global_load_lds_dwordx4 v[244:245], off
	s_waitcnt vmcnt(6)
	s_barrier
	v_mfma_f32_16x16x32_bf16 v[38:41], v[178:181], v[134:137], v[38:41]
	v_mfma_f32_16x16x32_bf16 v[34:37], v[186:189], v[134:137], v[34:37]
	v_mfma_f32_16x16x32_bf16 v[22:25], v[178:181], v[150:153], v[22:25]
	v_mfma_f32_16x16x32_bf16 v[18:21], v[186:189], v[150:153], v[18:21]
	v_mfma_f32_16x16x32_bf16 v[6:9], v[178:181], v[170:173], v[6:9]
	v_mfma_f32_16x16x32_bf16 v[2:5], v[186:189], v[170:173], v[2:5]
	v_mfma_f32_16x16x32_bf16 v[50:53], v[178:181], v[118:121], v[86:89]
	v_mfma_f32_16x16x32_bf16 v[54:57], v[186:189], v[118:121], v[82:85]
	v_mfma_f32_16x16x32_bf16 v[38:41], v[182:185], v[146:149], v[38:41]
	v_mfma_f32_16x16x32_bf16 v[34:37], v[190:193], v[146:149], v[34:37]
	v_mfma_f32_16x16x32_bf16 v[22:25], v[182:185], v[154:157], v[22:25]
	v_mfma_f32_16x16x32_bf16 v[18:21], v[190:193], v[154:157], v[18:21]
	v_mfma_f32_16x16x32_bf16 v[6:9], v[182:185], v[174:177], v[6:9]
	v_mfma_f32_16x16x32_bf16 v[2:5], v[190:193], v[174:177], v[2:5]
	v_mfma_f32_16x16x32_bf16 v[50:53], v[182:185], v[130:133], v[50:53]
	v_mfma_f32_16x16x32_bf16 v[54:57], v[190:193], v[130:133], v[54:57]
	s_add_i32 s72, 0, 0x18000
	v_add_u32_e32 v1, s72, v223
	s_barrier
	ds_read_b128 v[58:61], v1
	ds_read_b128 v[62:65], v1 offset:1024
	ds_read_b128 v[82:85], v1 offset:2048
	ds_read_b128 v[86:89], v1 offset:3072
	s_add_u32 s42, s42, s4
	s_addc_u32 s43, s43, 0
	s_mov_b32 m0, s81
	v_lshl_add_u64 v[134:135], s[42:43], 0, v[202:203]
	ds_read_b128 v[118:121], v230 offset:32768
	ds_read_b128 v[130:133], v230 offset:33792
	ds_read_b128 v[146:149], v230 offset:34816
	ds_read_b128 v[154:157], v230 offset:35840
	ds_read_b128 v[170:173], v230 offset:36864
	ds_read_b128 v[174:177], v230 offset:37888
	ds_read_b128 v[178:181], v230 offset:38912
	ds_read_b128 v[182:185], v230 offset:39936
	global_load_lds_dwordx4 v[134:135], off
	v_lshl_add_u64 v[134:135], s[42:43], 0, v[200:201]
	s_mov_b32 m0, s82
	s_nop 0
	global_load_lds_dwordx4 v[134:135], off
	s_waitcnt lgkmcnt(8)
	s_barrier
	s_waitcnt lgkmcnt(0)
	s_waitcnt lgkmcnt(0)
	v_mfma_f32_16x16x32_bf16 v[134:137], v[58:61], v[118:121], v[166:169]
	v_mfma_f32_16x16x32_bf16 v[166:169], v[62:65], v[130:133], v[134:137]
	v_mfma_f32_16x16x32_bf16 v[134:137], v[82:85], v[118:121], v[162:165]
	v_mfma_f32_16x16x32_bf16 v[162:165], v[86:89], v[130:133], v[134:137]
	v_mfma_f32_16x16x32_bf16 v[134:137], v[58:61], v[146:149], v[142:145]
	v_mfma_f32_16x16x32_bf16 v[142:145], v[62:65], v[154:157], v[134:137]
	v_mfma_f32_16x16x32_bf16 v[134:137], v[82:85], v[146:149], v[138:141]
	v_mfma_f32_16x16x32_bf16 v[126:129], v[58:61], v[170:173], v[126:129]
	v_mfma_f32_16x16x32_bf16 v[122:125], v[82:85], v[170:173], v[122:125]
	v_mfma_f32_16x16x32_bf16 v[110:113], v[58:61], v[178:181], v[110:113]
	v_mfma_f32_16x16x32_bf16 v[106:109], v[82:85], v[178:181], v[106:109]
	v_mfma_f32_16x16x32_bf16 v[138:141], v[86:89], v[154:157], v[134:137]
	v_mfma_f32_16x16x32_bf16 v[126:129], v[62:65], v[174:177], v[126:129]
	v_mfma_f32_16x16x32_bf16 v[122:125], v[86:89], v[174:177], v[122:125]
	v_mfma_f32_16x16x32_bf16 v[110:113], v[62:65], v[182:185], v[110:113]
	v_mfma_f32_16x16x32_bf16 v[106:109], v[86:89], v[182:185], v[106:109]
	s_barrier
	s_add_i32 s42, 0, 0x1c000
	s_add_i32 s43, s72, s78
	v_add_u32_e32 v1, s42, v223
	v_lshl_add_u64 v[134:135], v[214:215], 0, s[22:23]
	s_mov_b32 m0, s43
	ds_read_b128 v[186:189], v1
	ds_read_b128 v[190:193], v1 offset:1024
	ds_read_b128 v[208:211], v1 offset:2048
	ds_read_b128 v[232:235], v1 offset:3072
	global_load_lds_dwordx4 v[134:135], off
	v_lshl_add_u64 v[134:135], v[236:237], 0, s[22:23]
	s_add_i32 m0, s43, 0x2000
	s_nop 0
	global_load_lds_dwordx4 v[134:135], off
	s_barrier
	s_waitcnt lgkmcnt(0)
	s_waitcnt lgkmcnt(0)
	v_mfma_f32_16x16x32_bf16 v[66:69], v[208:211], v[118:121], v[66:69]
	v_mfma_f32_16x16x32_bf16 v[134:137], v[186:189], v[118:121], v[158:161]
	v_mfma_f32_16x16x32_bf16 v[150:153], v[232:235], v[130:133], v[66:69]
	v_mfma_f32_16x16x32_bf16 v[66:69], v[186:189], v[146:149], v[70:73]
	v_mfma_f32_16x16x32_bf16 v[158:161], v[190:193], v[130:133], v[134:137]
	v_mfma_f32_16x16x32_bf16 v[134:137], v[190:193], v[154:157], v[66:69]
	v_mfma_f32_16x16x32_bf16 v[66:69], v[208:211], v[146:149], v[74:77]
	v_mfma_f32_16x16x32_bf16 v[130:133], v[232:235], v[154:157], v[66:69]
	v_mfma_f32_16x16x32_bf16 v[66:69], v[186:189], v[170:173], v[78:81]
	v_mfma_f32_16x16x32_bf16 v[118:121], v[190:193], v[174:177], v[66:69]
	v_mfma_f32_16x16x32_bf16 v[66:69], v[208:211], v[170:173], v[114:117]
	v_mfma_f32_16x16x32_bf16 v[114:117], v[232:235], v[174:177], v[66:69]
	v_mfma_f32_16x16x32_bf16 v[66:69], v[186:189], v[178:181], v[102:105]
	v_mfma_f32_16x16x32_bf16 v[102:105], v[190:193], v[182:185], v[66:69]
	v_mfma_f32_16x16x32_bf16 v[66:69], v[208:211], v[178:181], v[98:101]
	v_mfma_f32_16x16x32_bf16 v[98:101], v[232:235], v[182:185], v[66:69]
	s_mov_b32 m0, s86
	v_lshl_add_u64 v[178:179], v[238:239], 0, s[22:23]
	s_barrier
	s_nop 2
	ds_read_b128 v[66:69], v230 offset:49152
	ds_read_b128 v[70:73], v230 offset:50176
	ds_read_b128 v[74:77], v230 offset:51200
	ds_read_b128 v[78:81], v230 offset:52224
	ds_read_b128 v[146:149], v230 offset:53248
	ds_read_b128 v[154:157], v230 offset:54272
	ds_read_b128 v[170:173], v230 offset:55296
	ds_read_b128 v[174:177], v230 offset:56320
	global_load_lds_dwordx4 v[178:179], off
	v_lshl_add_u64 v[178:179], v[240:241], 0, s[22:23]
	s_mov_b32 m0, s87
	s_nop 0
	global_load_lds_dwordx4 v[178:179], off
	s_barrier
	s_waitcnt lgkmcnt(0)
	s_waitcnt lgkmcnt(0)
	v_mfma_f32_16x16x32_bf16 v[94:97], v[58:61], v[66:69], v[94:97]
	v_mfma_f32_16x16x32_bf16 v[90:93], v[82:85], v[66:69], v[90:93]
	v_mfma_f32_16x16x32_bf16 v[46:49], v[58:61], v[74:77], v[46:49]
	v_mfma_f32_16x16x32_bf16 v[42:45], v[82:85], v[74:77], v[42:45]
	v_mfma_f32_16x16x32_bf16 v[30:33], v[58:61], v[146:149], v[30:33]
	v_mfma_f32_16x16x32_bf16 v[26:29], v[82:85], v[146:149], v[26:29]
	v_mfma_f32_16x16x32_bf16 v[14:17], v[58:61], v[170:173], v[14:17]
	v_mfma_f32_16x16x32_bf16 v[10:13], v[82:85], v[170:173], v[10:13]
	v_mfma_f32_16x16x32_bf16 v[94:97], v[62:65], v[70:73], v[94:97]
	v_mfma_f32_16x16x32_bf16 v[90:93], v[86:89], v[70:73], v[90:93]
	v_mfma_f32_16x16x32_bf16 v[46:49], v[62:65], v[78:81], v[46:49]
	v_mfma_f32_16x16x32_bf16 v[42:45], v[86:89], v[78:81], v[42:45]
	v_mfma_f32_16x16x32_bf16 v[30:33], v[62:65], v[154:157], v[30:33]
	v_mfma_f32_16x16x32_bf16 v[26:29], v[86:89], v[154:157], v[26:29]
	v_mfma_f32_16x16x32_bf16 v[14:17], v[62:65], v[174:177], v[14:17]
	v_mfma_f32_16x16x32_bf16 v[10:13], v[86:89], v[174:177], v[10:13]
	s_barrier
	s_add_i32 s42, s42, s78
	v_lshl_add_u64 v[58:59], v[242:243], 0, s[22:23]
	s_mov_b32 m0, s42
	s_nop 0
	global_load_lds_dwordx4 v[58:59], off
	v_lshl_add_u64 v[58:59], v[244:245], 0, s[22:23]
	s_add_i32 m0, s42, 0x2000
	s_nop 0
	global_load_lds_dwordx4 v[58:59], off
	s_waitcnt vmcnt(6)
	s_barrier
	v_mfma_f32_16x16x32_bf16 v[50:53], v[186:189], v[66:69], v[50:53]
	v_mfma_f32_16x16x32_bf16 v[86:89], v[190:193], v[70:73], v[50:53]
	v_mfma_f32_16x16x32_bf16 v[50:53], v[208:211], v[66:69], v[54:57]
	v_mfma_f32_16x16x32_bf16 v[38:41], v[186:189], v[74:77], v[38:41]
	v_mfma_f32_16x16x32_bf16 v[34:37], v[208:211], v[74:77], v[34:37]
	v_mfma_f32_16x16x32_bf16 v[22:25], v[186:189], v[146:149], v[22:25]
	v_mfma_f32_16x16x32_bf16 v[18:21], v[208:211], v[146:149], v[18:21]
	v_mfma_f32_16x16x32_bf16 v[6:9], v[186:189], v[170:173], v[6:9]
	v_mfma_f32_16x16x32_bf16 v[2:5], v[208:211], v[170:173], v[2:5]
	v_mfma_f32_16x16x32_bf16 v[82:85], v[232:235], v[70:73], v[50:53]
	v_mfma_f32_16x16x32_bf16 v[38:41], v[190:193], v[78:81], v[38:41]
	v_mfma_f32_16x16x32_bf16 v[34:37], v[232:235], v[78:81], v[34:37]
	v_mfma_f32_16x16x32_bf16 v[22:25], v[190:193], v[154:157], v[22:25]
	v_mfma_f32_16x16x32_bf16 v[18:21], v[232:235], v[154:157], v[18:21]
	v_mfma_f32_16x16x32_bf16 v[6:9], v[190:193], v[174:177], v[6:9]
	v_mfma_f32_16x16x32_bf16 v[2:5], v[232:235], v[174:177], v[2:5]
	s_add_u32 s27, s27, 0x100
	s_addc_u32 s91, s91, 0
	s_add_u32 s36, s36, 0x100
	s_addc_u32 s37, s37, 0
	s_cmp_ge_u32 s92, s32
	s_mov_b32 s42, s92
	s_barrier
	s_cbranch_scc0 .LBB0_1179
	s_cmp_eq_u32 s32, s84
	s_cbranch_scc1 .Ltail_done_1
	s_add_i32 s92, s42, 2
	s_add_u32 s72, s36, 0x80
	s_addc_u32 s43, s37, 0
	s_add_i32 s93, 0, 0x10000
	v_add_u32_e32 v1, s93, v223
	ds_read_b128 v[50:53], v1
	ds_read_b128 v[54:57], v1 offset:1024
	ds_read_b128 v[58:61], v1 offset:2048
	ds_read_b128 v[62:65], v1 offset:3072
	s_cmp_eq_u32 s88, s42
	s_cselect_b32 s42, s66, s72
	s_cselect_b32 s43, s67, s43
	s_cselect_b32 s73, s71, s91
	s_cselect_b32 s72, s70, s27
	v_lshl_add_u64 v[178:179], s[36:37], 0, v[206:207]
	s_add_i32 m0, s79, 0xc000
	ds_read_b128 v[66:69], v230
	ds_read_b128 v[70:73], v230 offset:1024
	ds_read_b128 v[74:77], v230 offset:2048
	ds_read_b128 v[78:81], v230 offset:3072
	ds_read_b128 v[146:149], v230 offset:4096
	ds_read_b128 v[154:157], v230 offset:5120
	ds_read_b128 v[170:173], v230 offset:6144
	ds_read_b128 v[174:177], v230 offset:7168
	global_load_lds_dwordx4 v[178:179], off
	v_lshl_add_u64 v[178:179], s[36:37], 0, v[204:205]
	s_add_i32 m0, s79, 0xe000
	s_nop 0
	global_load_lds_dwordx4 v[178:179], off
	s_waitcnt lgkmcnt(8)
	s_barrier
	s_waitcnt lgkmcnt(0)
	s_waitcnt lgkmcnt(0)
	v_mfma_f32_16x16x32_bf16 v[166:169], v[50:53], v[66:69], v[166:169]
	v_mfma_f32_16x16x32_bf16 v[162:165], v[58:61], v[66:69], v[162:165]
	v_mfma_f32_16x16x32_bf16 v[142:145], v[50:53], v[74:77], v[142:145]
	v_mfma_f32_16x16x32_bf16 v[138:141], v[58:61], v[74:77], v[138:141]
	v_mfma_f32_16x16x32_bf16 v[126:129], v[50:53], v[146:149], v[126:129]
	v_mfma_f32_16x16x32_bf16 v[122:125], v[58:61], v[146:149], v[122:125]
	v_mfma_f32_16x16x32_bf16 v[110:113], v[50:53], v[170:173], v[110:113]
	v_mfma_f32_16x16x32_bf16 v[106:109], v[58:61], v[170:173], v[106:109]
	v_mfma_f32_16x16x32_bf16 v[166:169], v[54:57], v[70:73], v[166:169]
	v_mfma_f32_16x16x32_bf16 v[162:165], v[62:65], v[70:73], v[162:165]
	v_mfma_f32_16x16x32_bf16 v[142:145], v[54:57], v[78:81], v[142:145]
	v_mfma_f32_16x16x32_bf16 v[138:141], v[62:65], v[78:81], v[138:141]
	v_mfma_f32_16x16x32_bf16 v[126:129], v[54:57], v[154:157], v[126:129]
	v_mfma_f32_16x16x32_bf16 v[122:125], v[62:65], v[154:157], v[122:125]
	v_mfma_f32_16x16x32_bf16 v[110:113], v[54:57], v[174:177], v[110:113]
	v_mfma_f32_16x16x32_bf16 v[106:109], v[62:65], v[174:177], v[106:109]
	s_barrier
	s_add_i32 s94, 0, 0x14000
	s_add_i32 s93, s93, s78
	v_add_u32_e32 v1, s94, v223
	v_lshl_add_u64 v[214:215], s[72:73], 0, v[202:203]
	s_mov_b32 m0, s93
	ds_read_b128 v[178:181], v1
	ds_read_b128 v[182:185], v1 offset:1024
	ds_read_b128 v[186:189], v1 offset:2048
	ds_read_b128 v[190:193], v1 offset:3072
	v_lshl_add_u64 v[236:237], s[72:73], 0, v[200:201]
	s_add_i32 m0, s93, 0x2000
	s_nop 0
	s_barrier
	s_waitcnt lgkmcnt(0)
	s_waitcnt lgkmcnt(0)
	v_mfma_f32_16x16x32_bf16 v[158:161], v[178:181], v[66:69], v[158:161]
	v_mfma_f32_16x16x32_bf16 v[66:69], v[186:189], v[66:69], v[150:153]
	v_mfma_f32_16x16x32_bf16 v[158:161], v[182:185], v[70:73], v[158:161]
	v_mfma_f32_16x16x32_bf16 v[66:69], v[190:193], v[70:73], v[66:69]
	v_mfma_f32_16x16x32_bf16 v[70:73], v[178:181], v[74:77], v[134:137]
	v_mfma_f32_16x16x32_bf16 v[74:77], v[186:189], v[74:77], v[130:133]
	v_mfma_f32_16x16x32_bf16 v[114:117], v[186:189], v[146:149], v[114:117]
	v_mfma_f32_16x16x32_bf16 v[102:105], v[178:181], v[170:173], v[102:105]
	v_mfma_f32_16x16x32_bf16 v[98:101], v[186:189], v[170:173], v[98:101]
	v_mfma_f32_16x16x32_bf16 v[70:73], v[182:185], v[78:81], v[70:73]
	v_mfma_f32_16x16x32_bf16 v[74:77], v[190:193], v[78:81], v[74:77]
	v_mfma_f32_16x16x32_bf16 v[78:81], v[178:181], v[146:149], v[118:121]
	v_mfma_f32_16x16x32_bf16 v[114:117], v[190:193], v[154:157], v[114:117]
	v_mfma_f32_16x16x32_bf16 v[102:105], v[182:185], v[174:177], v[102:105]
	v_mfma_f32_16x16x32_bf16 v[98:101], v[190:193], v[174:177], v[98:101]
	v_mfma_f32_16x16x32_bf16 v[78:81], v[182:185], v[154:157], v[78:81]
	s_mov_b32 m0, s79
	v_lshl_add_u64 v[238:239], s[42:43], 0, v[202:203]
	s_barrier
	ds_read_b128 v[118:121], v230 offset:16384
	ds_read_b128 v[130:133], v230 offset:17408
	ds_read_b128 v[134:137], v230 offset:18432
	ds_read_b128 v[146:149], v230 offset:19456
	ds_read_b128 v[150:153], v230 offset:20480
	ds_read_b128 v[154:157], v230 offset:21504
	ds_read_b128 v[170:173], v230 offset:22528
	ds_read_b128 v[174:177], v230 offset:23552
	v_lshl_add_u64 v[240:241], s[42:43], 0, v[200:201]
	s_mov_b32 m0, s80
	s_nop 0
	s_barrier
	s_waitcnt lgkmcnt(0)
	s_waitcnt lgkmcnt(0)
	v_mfma_f32_16x16x32_bf16 v[94:97], v[50:53], v[118:121], v[94:97]
	v_mfma_f32_16x16x32_bf16 v[90:93], v[58:61], v[118:121], v[90:93]
	v_mfma_f32_16x16x32_bf16 v[46:49], v[50:53], v[134:137], v[46:49]
	v_mfma_f32_16x16x32_bf16 v[42:45], v[58:61], v[134:137], v[42:45]
	v_mfma_f32_16x16x32_bf16 v[30:33], v[50:53], v[150:153], v[30:33]
	v_mfma_f32_16x16x32_bf16 v[26:29], v[58:61], v[150:153], v[26:29]
	v_mfma_f32_16x16x32_bf16 v[14:17], v[50:53], v[170:173], v[14:17]
	v_mfma_f32_16x16x32_bf16 v[10:13], v[58:61], v[170:173], v[10:13]
	v_mfma_f32_16x16x32_bf16 v[94:97], v[54:57], v[130:133], v[94:97]
	v_mfma_f32_16x16x32_bf16 v[90:93], v[62:65], v[130:133], v[90:93]
	v_mfma_f32_16x16x32_bf16 v[46:49], v[54:57], v[146:149], v[46:49]
	v_mfma_f32_16x16x32_bf16 v[42:45], v[62:65], v[146:149], v[42:45]
	v_mfma_f32_16x16x32_bf16 v[30:33], v[54:57], v[154:157], v[30:33]
	v_mfma_f32_16x16x32_bf16 v[26:29], v[62:65], v[154:157], v[26:29]
	v_mfma_f32_16x16x32_bf16 v[14:17], v[54:57], v[174:177], v[14:17]
	v_mfma_f32_16x16x32_bf16 v[10:13], v[62:65], v[174:177], v[10:13]
	s_barrier
	s_add_u32 s72, s72, s4
	s_addc_u32 s73, s73, 0
	s_add_i32 s93, s94, s78
	v_lshl_add_u64 v[242:243], s[72:73], 0, v[202:203]
	s_mov_b32 m0, s93
	v_lshl_add_u64 v[244:245], s[72:73], 0, v[200:201]
	s_add_i32 m0, s93, 0x2000
	s_nop 0
	s_waitcnt vmcnt(0)
	s_barrier
	v_mfma_f32_16x16x32_bf16 v[38:41], v[178:181], v[134:137], v[38:41]
	v_mfma_f32_16x16x32_bf16 v[34:37], v[186:189], v[134:137], v[34:37]
	v_mfma_f32_16x16x32_bf16 v[22:25], v[178:181], v[150:153], v[22:25]
	v_mfma_f32_16x16x32_bf16 v[18:21], v[186:189], v[150:153], v[18:21]
	v_mfma_f32_16x16x32_bf16 v[6:9], v[178:181], v[170:173], v[6:9]
	v_mfma_f32_16x16x32_bf16 v[2:5], v[186:189], v[170:173], v[2:5]
	v_mfma_f32_16x16x32_bf16 v[50:53], v[178:181], v[118:121], v[86:89]
	v_mfma_f32_16x16x32_bf16 v[54:57], v[186:189], v[118:121], v[82:85]
	v_mfma_f32_16x16x32_bf16 v[38:41], v[182:185], v[146:149], v[38:41]
	v_mfma_f32_16x16x32_bf16 v[34:37], v[190:193], v[146:149], v[34:37]
	v_mfma_f32_16x16x32_bf16 v[22:25], v[182:185], v[154:157], v[22:25]
	v_mfma_f32_16x16x32_bf16 v[18:21], v[190:193], v[154:157], v[18:21]
	v_mfma_f32_16x16x32_bf16 v[6:9], v[182:185], v[174:177], v[6:9]
	v_mfma_f32_16x16x32_bf16 v[2:5], v[190:193], v[174:177], v[2:5]
	v_mfma_f32_16x16x32_bf16 v[50:53], v[182:185], v[130:133], v[50:53]
	v_mfma_f32_16x16x32_bf16 v[54:57], v[190:193], v[130:133], v[54:57]
	s_add_i32 s72, 0, 0x18000
	v_add_u32_e32 v1, s72, v223
	s_barrier
	ds_read_b128 v[58:61], v1
	ds_read_b128 v[62:65], v1 offset:1024
	ds_read_b128 v[82:85], v1 offset:2048
	ds_read_b128 v[86:89], v1 offset:3072
	s_add_u32 s42, s42, s4
	s_addc_u32 s43, s43, 0
	s_mov_b32 m0, s81
	v_lshl_add_u64 v[134:135], s[42:43], 0, v[202:203]
	ds_read_b128 v[118:121], v230 offset:32768
	ds_read_b128 v[130:133], v230 offset:33792
	ds_read_b128 v[146:149], v230 offset:34816
	ds_read_b128 v[154:157], v230 offset:35840
	ds_read_b128 v[170:173], v230 offset:36864
	ds_read_b128 v[174:177], v230 offset:37888
	ds_read_b128 v[178:181], v230 offset:38912
	ds_read_b128 v[182:185], v230 offset:39936
	v_lshl_add_u64 v[134:135], s[42:43], 0, v[200:201]
	s_mov_b32 m0, s82
	s_nop 0
	s_waitcnt lgkmcnt(8)
	s_barrier
	s_waitcnt lgkmcnt(0)
	s_waitcnt lgkmcnt(0)
	v_mfma_f32_16x16x32_bf16 v[134:137], v[58:61], v[118:121], v[166:169]
	v_mfma_f32_16x16x32_bf16 v[166:169], v[62:65], v[130:133], v[134:137]
	v_mfma_f32_16x16x32_bf16 v[134:137], v[82:85], v[118:121], v[162:165]
	v_mfma_f32_16x16x32_bf16 v[162:165], v[86:89], v[130:133], v[134:137]
	v_mfma_f32_16x16x32_bf16 v[134:137], v[58:61], v[146:149], v[142:145]
	v_mfma_f32_16x16x32_bf16 v[142:145], v[62:65], v[154:157], v[134:137]
	v_mfma_f32_16x16x32_bf16 v[134:137], v[82:85], v[146:149], v[138:141]
	v_mfma_f32_16x16x32_bf16 v[126:129], v[58:61], v[170:173], v[126:129]
	v_mfma_f32_16x16x32_bf16 v[122:125], v[82:85], v[170:173], v[122:125]
	v_mfma_f32_16x16x32_bf16 v[110:113], v[58:61], v[178:181], v[110:113]
	v_mfma_f32_16x16x32_bf16 v[106:109], v[82:85], v[178:181], v[106:109]
	v_mfma_f32_16x16x32_bf16 v[138:141], v[86:89], v[154:157], v[134:137]
	v_mfma_f32_16x16x32_bf16 v[126:129], v[62:65], v[174:177], v[126:129]
	v_mfma_f32_16x16x32_bf16 v[122:125], v[86:89], v[174:177], v[122:125]
	v_mfma_f32_16x16x32_bf16 v[110:113], v[62:65], v[182:185], v[110:113]
	v_mfma_f32_16x16x32_bf16 v[106:109], v[86:89], v[182:185], v[106:109]
	s_barrier
	s_add_i32 s42, 0, 0x1c000
	s_add_i32 s43, s72, s78
	v_add_u32_e32 v1, s42, v223
	v_lshl_add_u64 v[134:135], v[214:215], 0, s[22:23]
	s_mov_b32 m0, s43
	ds_read_b128 v[186:189], v1
	ds_read_b128 v[190:193], v1 offset:1024
	ds_read_b128 v[208:211], v1 offset:2048
	ds_read_b128 v[232:235], v1 offset:3072
	v_lshl_add_u64 v[134:135], v[236:237], 0, s[22:23]
	s_add_i32 m0, s43, 0x2000
	s_nop 0
	s_barrier
	s_waitcnt lgkmcnt(0)
	s_waitcnt lgkmcnt(0)
	v_mfma_f32_16x16x32_bf16 v[66:69], v[208:211], v[118:121], v[66:69]
	v_mfma_f32_16x16x32_bf16 v[134:137], v[186:189], v[118:121], v[158:161]
	v_mfma_f32_16x16x32_bf16 v[150:153], v[232:235], v[130:133], v[66:69]
	v_mfma_f32_16x16x32_bf16 v[66:69], v[186:189], v[146:149], v[70:73]
	v_mfma_f32_16x16x32_bf16 v[158:161], v[190:193], v[130:133], v[134:137]
	v_mfma_f32_16x16x32_bf16 v[134:137], v[190:193], v[154:157], v[66:69]
	v_mfma_f32_16x16x32_bf16 v[66:69], v[208:211], v[146:149], v[74:77]
	v_mfma_f32_16x16x32_bf16 v[130:133], v[232:235], v[154:157], v[66:69]
	v_mfma_f32_16x16x32_bf16 v[66:69], v[186:189], v[170:173], v[78:81]
	v_mfma_f32_16x16x32_bf16 v[118:121], v[190:193], v[174:177], v[66:69]
	v_mfma_f32_16x16x32_bf16 v[66:69], v[208:211], v[170:173], v[114:117]
	v_mfma_f32_16x16x32_bf16 v[114:117], v[232:235], v[174:177], v[66:69]
	v_mfma_f32_16x16x32_bf16 v[66:69], v[186:189], v[178:181], v[102:105]
	v_mfma_f32_16x16x32_bf16 v[102:105], v[190:193], v[182:185], v[66:69]
	v_mfma_f32_16x16x32_bf16 v[66:69], v[208:211], v[178:181], v[98:101]
	v_mfma_f32_16x16x32_bf16 v[98:101], v[232:235], v[182:185], v[66:69]
	s_mov_b32 m0, s86
	v_lshl_add_u64 v[178:179], v[238:239], 0, s[22:23]
	s_barrier
	s_nop 2
	ds_read_b128 v[66:69], v230 offset:49152
	ds_read_b128 v[70:73], v230 offset:50176
	ds_read_b128 v[74:77], v230 offset:51200
	ds_read_b128 v[78:81], v230 offset:52224
	ds_read_b128 v[146:149], v230 offset:53248
	ds_read_b128 v[154:157], v230 offset:54272
	ds_read_b128 v[170:173], v230 offset:55296
	ds_read_b128 v[174:177], v230 offset:56320
	v_lshl_add_u64 v[178:179], v[240:241], 0, s[22:23]
	s_mov_b32 m0, s87
	s_nop 0
	s_barrier
	s_waitcnt lgkmcnt(0)
	s_waitcnt lgkmcnt(0)
	v_mfma_f32_16x16x32_bf16 v[94:97], v[58:61], v[66:69], v[94:97]
	v_mfma_f32_16x16x32_bf16 v[90:93], v[82:85], v[66:69], v[90:93]
	v_mfma_f32_16x16x32_bf16 v[46:49], v[58:61], v[74:77], v[46:49]
	v_mfma_f32_16x16x32_bf16 v[42:45], v[82:85], v[74:77], v[42:45]
	v_mfma_f32_16x16x32_bf16 v[30:33], v[58:61], v[146:149], v[30:33]
	v_mfma_f32_16x16x32_bf16 v[26:29], v[82:85], v[146:149], v[26:29]
	v_mfma_f32_16x16x32_bf16 v[14:17], v[58:61], v[170:173], v[14:17]
	v_mfma_f32_16x16x32_bf16 v[10:13], v[82:85], v[170:173], v[10:13]
	v_mfma_f32_16x16x32_bf16 v[94:97], v[62:65], v[70:73], v[94:97]
	v_mfma_f32_16x16x32_bf16 v[90:93], v[86:89], v[70:73], v[90:93]
	v_mfma_f32_16x16x32_bf16 v[46:49], v[62:65], v[78:81], v[46:49]
	v_mfma_f32_16x16x32_bf16 v[42:45], v[86:89], v[78:81], v[42:45]
	v_mfma_f32_16x16x32_bf16 v[30:33], v[62:65], v[154:157], v[30:33]
	v_mfma_f32_16x16x32_bf16 v[26:29], v[86:89], v[154:157], v[26:29]
	v_mfma_f32_16x16x32_bf16 v[14:17], v[62:65], v[174:177], v[14:17]
	v_mfma_f32_16x16x32_bf16 v[10:13], v[86:89], v[174:177], v[10:13]
	s_barrier
	s_add_i32 s42, s42, s78
	v_lshl_add_u64 v[58:59], v[242:243], 0, s[22:23]
	s_mov_b32 m0, s42
	s_nop 0
	v_lshl_add_u64 v[58:59], v[244:245], 0, s[22:23]
	s_add_i32 m0, s42, 0x2000
	s_nop 0
	s_barrier
	v_mfma_f32_16x16x32_bf16 v[50:53], v[186:189], v[66:69], v[50:53]
	v_mfma_f32_16x16x32_bf16 v[86:89], v[190:193], v[70:73], v[50:53]
	v_mfma_f32_16x16x32_bf16 v[50:53], v[208:211], v[66:69], v[54:57]
	v_mfma_f32_16x16x32_bf16 v[38:41], v[186:189], v[74:77], v[38:41]
	v_mfma_f32_16x16x32_bf16 v[34:37], v[208:211], v[74:77], v[34:37]
	v_mfma_f32_16x16x32_bf16 v[22:25], v[186:189], v[146:149], v[22:25]
	v_mfma_f32_16x16x32_bf16 v[18:21], v[208:211], v[146:149], v[18:21]
	v_mfma_f32_16x16x32_bf16 v[6:9], v[186:189], v[170:173], v[6:9]
	v_mfma_f32_16x16x32_bf16 v[2:5], v[208:211], v[170:173], v[2:5]
	v_mfma_f32_16x16x32_bf16 v[82:85], v[232:235], v[70:73], v[50:53]
	v_mfma_f32_16x16x32_bf16 v[38:41], v[190:193], v[78:81], v[38:41]
	v_mfma_f32_16x16x32_bf16 v[34:37], v[232:235], v[78:81], v[34:37]
	v_mfma_f32_16x16x32_bf16 v[22:25], v[190:193], v[154:157], v[22:25]
	v_mfma_f32_16x16x32_bf16 v[18:21], v[232:235], v[154:157], v[18:21]
	v_mfma_f32_16x16x32_bf16 v[6:9], v[190:193], v[174:177], v[6:9]
	v_mfma_f32_16x16x32_bf16 v[2:5], v[232:235], v[174:177], v[2:5]
	s_add_u32 s27, s27, 0x100
	s_addc_u32 s91, s91, 0
	s_add_u32 s36, s36, 0x100
	s_addc_u32 s37, s37, 0
	s_cmp_ge_u32 s92, s84
	s_mov_b32 s42, s92
	s_barrier
.Ltail_done_1:
	s_setprio 0
	s_lshl_b32 s3, s3, 8
	s_add_i32 s27, s3, s85
	v_lshl_or_b32 v210, s38, 8, v224
	v_or_b32_e32 v146, s27, v221
	v_ashrrev_i32_e32 v147, 31, v146
	v_ashrrev_i32_e32 v211, 31, v210
	v_lshlrev_b64 v[50:51], 2, v[210:211]
	v_lshl_add_u64 v[208:209], v[210:211], 1, s[48:49]
	v_lshlrev_b64 v[148:149], 11, v[146:147]
	v_lshl_add_u64 v[52:53], s[52:53], 0, v[50:51]
	v_lshl_add_u64 v[54:55], s[54:55], 0, v[50:51]
	v_lshl_add_u64 v[148:149], v[208:209], 0, v[148:149]
	global_load_dwordx4 v[74:77], v[52:53], off
	global_load_dwordx4 v[66:69], v[52:53], off offset:16
	global_load_dwordx4 v[78:81], v[54:55], off
	global_load_dwordx4 v[70:73], v[54:55], off offset:16
	global_load_dwordx4 v[58:61], v[52:53], off offset:512
	s_nop 0
	global_load_dwordx4 v[50:53], v[52:53], off offset:528
	s_nop 0
	global_load_dwordx4 v[62:65], v[54:55], off offset:512
	s_nop 0
	global_load_dwordx4 v[54:57], v[54:55], off offset:528
	global_load_dwordx4 v[190:193], v[148:149], off
	global_load_dwordx4 v[186:189], v[148:149], off offset:256
	v_or_b32_e32 v148, 16, v146
	v_ashrrev_i32_e32 v149, 31, v148
	v_lshlrev_b64 v[148:149], 11, v[148:149]
	v_lshl_add_u64 v[148:149], v[208:209], 0, v[148:149]
	global_load_dwordx4 v[182:185], v[148:149], off
	global_load_dwordx4 v[178:181], v[148:149], off offset:256
	v_or_b32_e32 v148, 32, v146
	v_or_b32_e32 v146, 48, v146
	v_ashrrev_i32_e32 v149, 31, v148
	v_ashrrev_i32_e32 v147, 31, v146
	v_lshlrev_b64 v[148:149], 11, v[148:149]
	v_lshlrev_b64 v[146:147], 11, v[146:147]
	v_mov_b32_e32 v1, v222
	v_lshl_add_u64 v[148:149], v[208:209], 0, v[148:149]
	v_lshl_add_u64 v[146:147], v[208:209], 0, v[146:147]
	global_load_dwordx4 v[174:177], v[148:149], off
	global_load_dwordx4 v[170:173], v[148:149], off offset:256
	global_load_dwordx4 v[154:157], v[146:147], off
	s_nop 0
	global_load_dwordx4 v[146:149], v[146:147], off offset:256
	v_cndmask_b32_e64 v211, 0, 1, s[56:57]
	v_cmp_ne_u32_e64 s[42:43], 1, v211
	s_andn2_b64 vcc, exec, s[56:57]
	v_lshl_add_u32 v231, v1, 3, s33
	s_cbranch_vccnz .LBB0_1182
	ds_read_b64 v[214:215], v231
	s_waitcnt lgkmcnt(0)
	v_mov_b32_e32 v212, v215
	s_branch .LBB0_1183
